# phase 0 row pass software-pipelined: next iteration's row 0 loaded into shadow registers during row 1's compute; per-chunk waits removed
# speedup vs baseline: 1.0169x; 1.0043x over previous
.LBB0_176:
	s_or_b64 exec, exec, s[4:5]
	v_ashrrev_i32_e32 v0, 6, v8
	v_lshl_add_u32 v46, s2, 3, v0
	s_movk_i32 s2, 0x4a00
	v_cmp_gt_i32_e32 vcc, s2, v46
	s_waitcnt lgkmcnt(0)
	s_barrier
	s_and_saveexec_b64 s[12:13], vcc
	s_cbranch_execz .LBB0_229
	s_add_u32 s3, s24, 0x4e24000
	s_addc_u32 s10, s25, 0
	s_add_u32 s11, s26, 0x1830000
	s_addc_u32 s33, s27, 0
	s_add_u32 s14, s26, 0x1600000
	s_addc_u32 s15, s27, 0
	v_and_b32_e32 v0, 63, v8
	s_add_u32 s16, s26, 0x1612800
	v_lshlrev_b32_e32 v40, 2, v0
	v_mul_u32_u24_e32 v41, 0x90, v0
	s_addc_u32 s17, s27, 0
	s_lshl_b32 s42, s34, 3
	v_mov_b32_e32 v43, 0
	v_cmp_eq_u32_e64 s[4:5], 0, v0
	v_add_u32_e32 v52, 0x2400, v41
	v_add_u32_e32 v53, 0x4800, v41
	v_add_u32_e32 v54, 0x6c00, v41
	s_mov_b64 s[18:19], 0
	s_movk_i32 s43, 0x3fff
	s_movk_i32 s56, 0x41ff
	v_lshlrev_b32_e32 v42, 2, v40
	s_movk_i32 s57, 0x4200
	s_movk_i32 s58, 0x7fff
	v_mov_b32_e32 v55, 0x358637bd
	s_mov_b32 s59, 0x800000
	s_movk_i32 s60, 0x49ff
	v_mov_b32_e32 v56, 1
	v_readfirstlane_b32 s98, v46
	s_cmp_gt_i32 s98, s43
	s_cbranch_scc1 .Lrpa_1
	s_mov_b64 s[100:101], s[20:21]
	s_mov_b32 s99, s98
	s_branch .Lrpa_3
.Lrpa_1:
	s_cmp_gt_i32 s98, s56
	s_cbranch_scc1 .Lrpa_2
	s_mov_b64 s[100:101], s[22:23]
	s_add_i32 s99, s98, 0xffffc000
	s_branch .Lrpa_3
.Lrpa_2:
	s_mov_b64 s[100:101], s[46:47]
	s_add_i32 s99, s98, 0xffffbe00
.Lrpa_3:
	s_lshl_b32 s99, s99, 12
	s_add_u32 s100, s100, s99
	s_addc_u32 s101, s101, 0
	global_load_dwordx4 v[160:163], v42, s[100:101] nt
	global_load_dwordx4 v[164:167], v42, s[100:101] offset:1024 nt
	global_load_dwordx4 v[168:171], v42, s[100:101] offset:2048 nt
	global_load_dwordx4 v[172:175], v42, s[100:101] offset:3072 nt
	s_branch .LBB0_179

.LBB0_185:
	s_or_saveexec_b64 s[6:7], s[6:7]
	v_ashrrev_i32_e32 v47, 31, v46
	s_xor_b64 exec, exec, s[6:7]
	v_mov_b64_e32 v[2:3], v[46:47]
	s_or_b64 exec, exec, s[6:7]
	v_lshlrev_b64 v[2:3], 12, v[2:3]
	v_lshl_add_u64 v[0:1], v[0:1], 0, v[2:3]
	v_lshl_add_u64 v[0:1], v[0:1], 0, v[42:43]
	s_waitcnt vmcnt(0)
	v_mov_b32_e32 v36, v160
	v_mov_b32_e32 v37, v161
	v_mov_b32_e32 v38, v162
	v_mov_b32_e32 v39, v163
	v_mov_b32_e32 v32, v164
	v_mov_b32_e32 v33, v165
	v_mov_b32_e32 v34, v166
	v_mov_b32_e32 v35, v167
	v_mov_b32_e32 v28, v168
	v_mov_b32_e32 v29, v169
	v_mov_b32_e32 v30, v170
	v_mov_b32_e32 v31, v171
	v_mov_b32_e32 v24, v172
	v_mov_b32_e32 v25, v173
	v_mov_b32_e32 v26, v174
	v_mov_b32_e32 v27, v175
	v_add_u32_e32 v44, s42, v46
	v_cmp_gt_i32_e64 s[6:7], s2, v44
	s_and_saveexec_b64 s[8:9], s[6:7]
	s_cbranch_execz .LBB0_197
	v_cmp_lt_i32_e32 vcc, s43, v44
	v_mov_b64_e32 v[0:1], s[20:21]
	s_and_saveexec_b64 s[24:25], vcc
	s_xor_b64 s[24:25], exec, s[24:25]
	s_cbranch_execz .LBB0_194
	v_cmp_lt_u32_e32 vcc, s56, v44
	v_mov_b64_e32 v[0:1], s[22:23]
	s_and_saveexec_b64 s[28:29], vcc
	s_xor_b64 s[28:29], exec, s[28:29]
	v_add_u32_e32 v2, 0xffffbe00, v44
	v_mov_b32_e32 v3, v43
	v_mov_b64_e32 v[0:1], s[46:47]
	s_andn2_saveexec_b64 s[28:29], s[28:29]
	v_add_u32_e32 v2, 0xffffc000, v44
	v_mov_b32_e32 v3, v43
	s_or_b64 exec, exec, s[28:29]

.LBB0_197:
	s_or_b64 exec, exec, s[8:9]
	v_add_u32_e32 v0, 0xffffbe00, v46
	v_cmp_gt_i32_e64 s[8:9], s57, v46
	v_mov_b32_e32 v2, s33
	v_mov_b32_e32 v3, s10
	v_cndmask_b32_e64 v1, 0, v47, s[8:9]
	v_cndmask_b32_e64 v0, v0, v46, s[8:9]
	v_cndmask_b32_e64 v3, v2, v3, s[8:9]
	v_mov_b32_e32 v2, s11
	v_mov_b32_e32 v4, s3
	v_cndmask_b32_e64 v2, v2, v4, s[8:9]
	v_lshlrev_b64 v[0:1], 11, v[0:1]
	v_lshl_add_u64 v[0:1], v[2:3], 0, v[0:1]
	v_and_b32_sdwa v3, v36, v56 dst_sel:DWORD dst_unused:UNUSED_PAD src0_sel:WORD_1 src1_sel:DWORD
	v_add3_u32 v4, v36, v3, s58
	v_and_b32_sdwa v3, v39, v56 dst_sel:DWORD dst_unused:UNUSED_PAD src0_sel:WORD_1 src1_sel:DWORD
	v_and_b32_sdwa v5, v37, v56 dst_sel:DWORD dst_unused:UNUSED_PAD src0_sel:WORD_1 src1_sel:DWORD
	v_and_b32_sdwa v2, v38, v56 dst_sel:DWORD dst_unused:UNUSED_PAD src0_sel:WORD_1 src1_sel:DWORD
	v_add3_u32 v3, v39, v3, s58
	v_add3_u32 v5, v37, v5, s58
	v_add3_u32 v2, v38, v2, s58
	v_and_b32_e32 v3, 0xffff0000, v3
	v_and_b32_e32 v5, 0xffff0000, v5
	v_lshlrev_b32_e32 v48, 1, v40
	v_mov_b32_e32 v49, v43
	v_or_b32_sdwa v3, v3, v2 dst_sel:DWORD dst_unused:UNUSED_PAD src0_sel:DWORD src1_sel:WORD_1
	v_or_b32_sdwa v2, v5, v4 dst_sel:DWORD dst_unused:UNUSED_PAD src0_sel:DWORD src1_sel:WORD_1
	v_lshl_add_u64 v[50:51], v[0:1], 0, v[48:49]
	v_cmp_lt_i32_e32 vcc, s56, v46
	global_store_dwordx2 v[50:51], v[2:3], off
	v_mov_b32_e32 v0, v43
	v_mov_b32_e32 v1, v43
	v_mov_b32_e32 v2, v43
	v_mov_b32_e32 v3, v43
	v_mov_b32_e32 v4, v43
	v_mov_b32_e32 v5, v43
	v_mov_b32_e32 v6, v43
	v_mov_b32_e32 v7, v43
	v_add_u32_e32 v57, 0, v41
	s_and_saveexec_b64 s[24:25], s[8:9]
	s_cbranch_execz .LBB0_199
	ds_read_b128 v[0:3], v57 offset:16
	ds_read_b128 v[4:7], v57 offset:48
	ds_read_b128 v[58:61], v57
	ds_read_b128 v[62:65], v57 offset:32
	ds_read_b128 v[66:69], v57 offset:64
	ds_read_b128 v[70:73], v57 offset:80
	ds_read_b128 v[74:77], v57 offset:96
	ds_read_b128 v[78:81], v57 offset:112
	s_waitcnt lgkmcnt(7)
	v_mul_f32_e32 v2, v36, v2
	s_waitcnt lgkmcnt(6)
	v_mul_f32_e32 v82, v37, v6
	v_mov_b32_e32 v6, v3
	v_pk_mul_f32 v[6:7], v[36:37], v[6:7]
	s_waitcnt lgkmcnt(0)
	v_mul_f32_e32 v86, v39, v80
	v_mov_b32_e32 v80, v73
	v_mov_b32_e32 v3, v6
	v_pk_mul_f32 v[80:81], v[38:39], v[80:81]
	v_pk_add_f32 v[2:3], v[2:3], 0 op_sel_hi:[1,0]
	v_pk_fma_f32 v[60:61], v[36:37], v[60:61], 0 op_sel_hi:[0,1,0]
	v_pk_fma_f32 v[58:59], v[36:37], v[58:59], 0 op_sel_hi:[0,1,0]
	v_pk_fma_f32 v[0:1], v[36:37], v[0:1], 0 op_sel_hi:[0,1,0]
	v_mov_b32_e32 v83, v7
	v_mul_f32_e32 v72, v38, v72
	v_pk_fma_f32 v[60:61], v[36:37], v[64:65], v[60:61] op_sel:[1,0,0]
	v_pk_add_f32 v[2:3], v[2:3], v[82:83]
	v_pk_fma_f32 v[0:1], v[36:37], v[4:5], v[0:1] op_sel:[1,0,0]
	v_pk_fma_f32 v[4:5], v[36:37], v[62:63], v[58:59] op_sel:[1,0,0]
	v_mov_b32_e32 v73, v80
	v_mov_b32_e32 v84, v39
	v_pk_add_f32 v[6:7], v[2:3], v[72:73]
	v_pk_fma_f32 v[2:3], v[38:39], v[68:69], v[60:61] op_sel_hi:[0,1,1]
	v_pk_fma_f32 v[58:59], v[38:39], v[66:67], v[4:5] op_sel_hi:[0,1,1]
	v_pk_fma_f32 v[0:1], v[38:39], v[70:71], v[0:1] op_sel_hi:[0,1,1]
	v_mov_b32_e32 v87, v81
	v_pk_fma_f32 v[2:3], v[84:85], v[76:77], v[2:3] op_sel_hi:[0,1,1]
	v_pk_add_f32 v[6:7], v[6:7], v[86:87]
	v_pk_fma_f32 v[4:5], v[84:85], v[78:79], v[0:1] op_sel_hi:[0,1,1]
	v_pk_fma_f32 v[0:1], v[84:85], v[74:75], v[58:59] op_sel_hi:[0,1,1]
.LBB0_199:
	s_or_b64 exec, exec, s[24:25]
	v_and_b32_sdwa v58, v35, v56 dst_sel:DWORD dst_unused:UNUSED_PAD src0_sel:WORD_1 src1_sel:DWORD
	v_and_b32_sdwa v59, v33, v56 dst_sel:DWORD dst_unused:UNUSED_PAD src0_sel:WORD_1 src1_sel:DWORD
	v_and_b32_sdwa v45, v34, v56 dst_sel:DWORD dst_unused:UNUSED_PAD src0_sel:WORD_1 src1_sel:DWORD
	v_and_b32_sdwa v49, v32, v56 dst_sel:DWORD dst_unused:UNUSED_PAD src0_sel:WORD_1 src1_sel:DWORD
	v_add3_u32 v58, v35, v58, s58
	v_add3_u32 v59, v33, v59, s58
	v_add3_u32 v49, v32, v49, s58
	v_add3_u32 v45, v34, v45, s58
	v_and_b32_e32 v58, 0xffff0000, v58
	v_and_b32_e32 v60, 0xffff0000, v59
	v_or_b32_sdwa v59, v58, v45 dst_sel:DWORD dst_unused:UNUSED_PAD src0_sel:DWORD src1_sel:WORD_1
	v_or_b32_sdwa v58, v60, v49 dst_sel:DWORD dst_unused:UNUSED_PAD src0_sel:DWORD src1_sel:WORD_1
	global_store_dwordx2 v[50:51], v[58:59], off offset:512
	s_and_saveexec_b64 s[24:25], s[8:9]
	s_cbranch_execz .LBB0_201
	v_add_u32_e32 v45, 0, v52
	ds_read_b128 v[58:61], v45 offset:16
	ds_read_b128 v[62:65], v57 offset:9248
	ds_read_b128 v[66:69], v57 offset:9264
	ds_read_b128 v[70:73], v45
	ds_read_b128 v[74:77], v57 offset:9280
	ds_read_b128 v[78:81], v57 offset:9296
	ds_read_b128 v[82:85], v57 offset:9312
	ds_read_b128 v[86:89], v57 offset:9328
	s_waitcnt lgkmcnt(7)
	v_mul_f32_e32 v60, v32, v60
	s_waitcnt lgkmcnt(5)
	v_mul_f32_e32 v90, v33, v68
	v_mov_b32_e32 v68, v61
	v_pk_mul_f32 v[68:69], v[32:33], v[68:69]
	s_waitcnt lgkmcnt(0)
	v_mul_f32_e32 v94, v35, v88
	v_mov_b32_e32 v88, v81
	v_mov_b32_e32 v61, v68
	v_pk_mul_f32 v[88:89], v[34:35], v[88:89]
	v_pk_fma_f32 v[4:5], v[32:33], v[58:59], v[4:5] op_sel_hi:[0,1,1]
	v_pk_add_f32 v[6:7], v[6:7], v[60:61]
	v_pk_fma_f32 v[2:3], v[32:33], v[72:73], v[2:3] op_sel_hi:[0,1,1]
	v_pk_fma_f32 v[0:1], v[32:33], v[70:71], v[0:1] op_sel_hi:[0,1,1]
	v_mov_b32_e32 v91, v69
	v_mul_f32_e32 v80, v34, v80
	v_pk_fma_f32 v[2:3], v[32:33], v[64:65], v[2:3] op_sel:[1,0,0]
	v_pk_add_f32 v[6:7], v[6:7], v[90:91]
	v_pk_fma_f32 v[4:5], v[32:33], v[66:67], v[4:5] op_sel:[1,0,0]
	v_pk_fma_f32 v[0:1], v[32:33], v[62:63], v[0:1] op_sel:[1,0,0]
	v_mov_b32_e32 v81, v88
	v_mov_b32_e32 v92, v35
	v_pk_add_f32 v[6:7], v[6:7], v[80:81]
	v_pk_fma_f32 v[2:3], v[34:35], v[76:77], v[2:3] op_sel_hi:[0,1,1]
	v_pk_fma_f32 v[0:1], v[34:35], v[74:75], v[0:1] op_sel_hi:[0,1,1]
	v_pk_fma_f32 v[4:5], v[34:35], v[78:79], v[4:5] op_sel_hi:[0,1,1]
	v_mov_b32_e32 v95, v89
	v_pk_fma_f32 v[2:3], v[92:93], v[84:85], v[2:3] op_sel_hi:[0,1,1]
	v_pk_add_f32 v[6:7], v[6:7], v[94:95]
	v_pk_fma_f32 v[4:5], v[92:93], v[86:87], v[4:5] op_sel_hi:[0,1,1]
	v_pk_fma_f32 v[0:1], v[92:93], v[82:83], v[0:1] op_sel_hi:[0,1,1]
.LBB0_201:
	s_or_b64 exec, exec, s[24:25]
	v_and_b32_sdwa v58, v31, v56 dst_sel:DWORD dst_unused:UNUSED_PAD src0_sel:WORD_1 src1_sel:DWORD
	v_and_b32_sdwa v59, v29, v56 dst_sel:DWORD dst_unused:UNUSED_PAD src0_sel:WORD_1 src1_sel:DWORD
	v_and_b32_sdwa v45, v30, v56 dst_sel:DWORD dst_unused:UNUSED_PAD src0_sel:WORD_1 src1_sel:DWORD
	v_and_b32_sdwa v49, v28, v56 dst_sel:DWORD dst_unused:UNUSED_PAD src0_sel:WORD_1 src1_sel:DWORD
	v_add3_u32 v58, v31, v58, s58
	v_add3_u32 v59, v29, v59, s58
	v_add3_u32 v49, v28, v49, s58
	v_add3_u32 v45, v30, v45, s58
	v_and_b32_e32 v58, 0xffff0000, v58
	v_and_b32_e32 v60, 0xffff0000, v59
	v_or_b32_sdwa v59, v58, v45 dst_sel:DWORD dst_unused:UNUSED_PAD src0_sel:DWORD src1_sel:WORD_1
	v_or_b32_sdwa v58, v60, v49 dst_sel:DWORD dst_unused:UNUSED_PAD src0_sel:DWORD src1_sel:WORD_1
	global_store_dwordx2 v[50:51], v[58:59], off offset:1024
	s_and_saveexec_b64 s[24:25], s[8:9]
	s_cbranch_execz .LBB0_203
	v_add_u32_e32 v45, 0, v53
	ds_read_b128 v[58:61], v45 offset:16
	ds_read_b128 v[62:65], v57 offset:18464
	ds_read_b128 v[66:69], v57 offset:18480
	ds_read_b128 v[70:73], v45
	ds_read_b128 v[74:77], v57 offset:18496
	ds_read_b128 v[78:81], v57 offset:18512
	ds_read_b128 v[82:85], v57 offset:18528
	ds_read_b128 v[86:89], v57 offset:18544
	s_waitcnt lgkmcnt(7)
	v_mul_f32_e32 v60, v28, v60
	s_waitcnt lgkmcnt(5)
	v_mul_f32_e32 v90, v29, v68
	v_mov_b32_e32 v68, v61
	v_pk_mul_f32 v[68:69], v[28:29], v[68:69]
	s_waitcnt lgkmcnt(0)
	v_mul_f32_e32 v94, v31, v88
	v_mov_b32_e32 v88, v81
	v_mov_b32_e32 v61, v68
	v_pk_mul_f32 v[88:89], v[30:31], v[88:89]
	v_pk_fma_f32 v[4:5], v[28:29], v[58:59], v[4:5] op_sel_hi:[0,1,1]
	v_pk_add_f32 v[6:7], v[6:7], v[60:61]
	v_pk_fma_f32 v[2:3], v[28:29], v[72:73], v[2:3] op_sel_hi:[0,1,1]
	v_pk_fma_f32 v[0:1], v[28:29], v[70:71], v[0:1] op_sel_hi:[0,1,1]
	v_mov_b32_e32 v91, v69
	v_mul_f32_e32 v80, v30, v80
	v_pk_fma_f32 v[2:3], v[28:29], v[64:65], v[2:3] op_sel:[1,0,0]
	v_pk_add_f32 v[6:7], v[6:7], v[90:91]
	v_pk_fma_f32 v[4:5], v[28:29], v[66:67], v[4:5] op_sel:[1,0,0]
	v_pk_fma_f32 v[0:1], v[28:29], v[62:63], v[0:1] op_sel:[1,0,0]
	v_mov_b32_e32 v81, v88
	v_mov_b32_e32 v92, v31
	v_pk_add_f32 v[6:7], v[6:7], v[80:81]
	v_pk_fma_f32 v[2:3], v[30:31], v[76:77], v[2:3] op_sel_hi:[0,1,1]
	v_pk_fma_f32 v[0:1], v[30:31], v[74:75], v[0:1] op_sel_hi:[0,1,1]
	v_pk_fma_f32 v[4:5], v[30:31], v[78:79], v[4:5] op_sel_hi:[0,1,1]
	v_mov_b32_e32 v95, v89
	v_pk_fma_f32 v[2:3], v[92:93], v[84:85], v[2:3] op_sel_hi:[0,1,1]
	v_pk_add_f32 v[6:7], v[6:7], v[94:95]
	v_pk_fma_f32 v[4:5], v[92:93], v[86:87], v[4:5] op_sel_hi:[0,1,1]
	v_pk_fma_f32 v[0:1], v[92:93], v[82:83], v[0:1] op_sel_hi:[0,1,1]
.LBB0_203:
	s_or_b64 exec, exec, s[24:25]
	v_and_b32_sdwa v58, v27, v56 dst_sel:DWORD dst_unused:UNUSED_PAD src0_sel:WORD_1 src1_sel:DWORD
	v_and_b32_sdwa v59, v25, v56 dst_sel:DWORD dst_unused:UNUSED_PAD src0_sel:WORD_1 src1_sel:DWORD
	v_and_b32_sdwa v45, v26, v56 dst_sel:DWORD dst_unused:UNUSED_PAD src0_sel:WORD_1 src1_sel:DWORD
	v_and_b32_sdwa v49, v24, v56 dst_sel:DWORD dst_unused:UNUSED_PAD src0_sel:WORD_1 src1_sel:DWORD
	v_add3_u32 v58, v27, v58, s58
	v_add3_u32 v59, v25, v59, s58
	v_add3_u32 v49, v24, v49, s58
	v_add3_u32 v45, v26, v45, s58
	v_and_b32_e32 v58, 0xffff0000, v58
	v_and_b32_e32 v60, 0xffff0000, v59
	v_or_b32_sdwa v59, v58, v45 dst_sel:DWORD dst_unused:UNUSED_PAD src0_sel:DWORD src1_sel:WORD_1
	v_or_b32_sdwa v58, v60, v49 dst_sel:DWORD dst_unused:UNUSED_PAD src0_sel:DWORD src1_sel:WORD_1
	global_store_dwordx2 v[50:51], v[58:59], off offset:1536
	s_and_saveexec_b64 s[24:25], s[8:9]
	s_cbranch_execz .LBB0_205
	v_add_u32_e32 v45, 0, v54
	ds_read_b128 v[58:61], v45 offset:16
	ds_read_b128 v[62:65], v57 offset:27680
	ds_read_b128 v[66:69], v57 offset:27696
	ds_read_b128 v[70:73], v45
	ds_read_b128 v[74:77], v57 offset:27712
	ds_read_b128 v[78:81], v57 offset:27728
	ds_read_b128 v[82:85], v57 offset:27744
	ds_read_b128 v[86:89], v57 offset:27760
	s_waitcnt lgkmcnt(7)
	v_mul_f32_e32 v50, v24, v60
	s_waitcnt lgkmcnt(5)
	v_mul_f32_e32 v60, v25, v68
	v_mov_b32_e32 v68, v61
	v_pk_mul_f32 v[68:69], v[24:25], v[68:69]
	s_waitcnt lgkmcnt(0)
	v_mul_f32_e32 v92, v27, v88
	v_mov_b32_e32 v88, v81
	v_mov_b32_e32 v51, v68
	v_pk_mul_f32 v[88:89], v[26:27], v[88:89]
	v_pk_fma_f32 v[4:5], v[24:25], v[58:59], v[4:5] op_sel_hi:[0,1,1]
	v_pk_add_f32 v[6:7], v[6:7], v[50:51]
	v_pk_fma_f32 v[2:3], v[24:25], v[72:73], v[2:3] op_sel_hi:[0,1,1]
	v_pk_fma_f32 v[0:1], v[24:25], v[70:71], v[0:1] op_sel_hi:[0,1,1]
	v_mov_b32_e32 v61, v69
	v_mul_f32_e32 v80, v26, v80
	v_pk_fma_f32 v[2:3], v[24:25], v[64:65], v[2:3] op_sel:[1,0,0]
	v_pk_add_f32 v[6:7], v[6:7], v[60:61]
	v_pk_fma_f32 v[4:5], v[24:25], v[66:67], v[4:5] op_sel:[1,0,0]
	v_pk_fma_f32 v[0:1], v[24:25], v[62:63], v[0:1] op_sel:[1,0,0]
	v_mov_b32_e32 v81, v88
	v_mov_b32_e32 v90, v27
	v_pk_add_f32 v[6:7], v[6:7], v[80:81]
	v_pk_fma_f32 v[2:3], v[26:27], v[76:77], v[2:3] op_sel_hi:[0,1,1]
	v_pk_fma_f32 v[0:1], v[26:27], v[74:75], v[0:1] op_sel_hi:[0,1,1]
	v_pk_fma_f32 v[4:5], v[26:27], v[78:79], v[4:5] op_sel_hi:[0,1,1]
	v_mov_b32_e32 v93, v89
	v_pk_fma_f32 v[2:3], v[90:91], v[84:85], v[2:3] op_sel_hi:[0,1,1]
	v_pk_add_f32 v[6:7], v[6:7], v[92:93]
	v_pk_fma_f32 v[4:5], v[90:91], v[86:87], v[4:5] op_sel_hi:[0,1,1]
	v_pk_fma_f32 v[0:1], v[90:91], v[82:83], v[0:1] op_sel_hi:[0,1,1]

.LBB0_214:
	s_waitcnt vmcnt(4)
	v_readfirstlane_b32 s98, v44
	s_add_i32 s98, s98, s42
	s_cmp_gt_i32 s98, s60
	s_cbranch_scc1 .Lrpb_np
	s_cmp_gt_i32 s98, s43
	s_cbranch_scc1 .Lrpb_1
	s_mov_b64 s[100:101], s[20:21]
	s_mov_b32 s99, s98
	s_branch .Lrpb_3

.Lrpb_3:
	s_lshl_b32 s99, s99, 12
	s_add_u32 s100, s100, s99
	s_addc_u32 s101, s101, 0
	global_load_dwordx4 v[160:163], v42, s[100:101] nt
	global_load_dwordx4 v[164:167], v42, s[100:101] offset:1024 nt
	global_load_dwordx4 v[168:171], v42, s[100:101] offset:2048 nt
	global_load_dwordx4 v[172:175], v42, s[100:101] offset:3072 nt
